# P3 merge-gate epilogue: the -log2(e) factor of the sigmoid argument folded into the eight per-row rstd values (128 fewer VALU multiplies per wave and unit)
# speedup vs baseline: 1.0006x; 1.0006x over previous
.LBB0_1299:
	v_lshl_add_u32 v150, s20, 8, v1
	v_ashrrev_i32_e32 v151, 31, v150
	v_lshl_add_u64 v[170:171], v[150:151], 2, s[64:65]
	global_load_dword v172, v[170:171], off
	v_lshl_or_b32 v174, s42, 8, v153
	v_or_b32_e32 v176, 16, v150
	v_mov_b64_e32 v[146:147], s[68:69]
	v_or_b32_e32 v162, 32, v150
	v_or_b32_e32 v158, 48, v150
	v_ashrrev_i32_e32 v175, 31, v174
	v_ashrrev_i32_e32 v177, 31, v176
	v_add_u32_e32 v168, 0x80, v150
	v_add_u32_e32 v167, 0x90, v150
	v_add_u32_e32 v166, 0xa0, v150
	v_add_u32_e32 v165, 0xb0, v150
	v_mad_i64_i32 v[178:179], s[22:23], v150, s41, v[146:147]
	v_ashrrev_i32_e32 v163, 31, v162
	v_ashrrev_i32_e32 v159, 31, v158
	v_lshlrev_b64 v[150:151], 1, v[174:175]
	v_lshl_add_u64 v[174:175], v[176:177], 2, s[64:65]
	v_lshl_add_u64 v[180:181], v[162:163], 2, s[64:65]
	v_lshl_add_u64 v[182:183], v[158:159], 2, s[64:65]
	global_load_dword v156, v[170:171], off offset:512
	global_load_dword v154, v[170:171], off offset:576
	global_load_dword v152, v[170:171], off offset:640
	s_nop 0
	global_load_dword v174, v[174:175], off
	s_nop 0
	global_load_dword v164, v[180:181], off
	global_load_dword v160, v[182:183], off
	global_load_dword v148, v[170:171], off offset:704
	v_lshl_add_u64 v[178:179], v[178:179], 0, v[150:151]
	s_andn2_b64 vcc, exec, s[4:5]
	s_mov_b64 s[4:5], -1
	s_waitcnt vmcnt(0)
	v_mul_f32_e32 v148, 0xbfb8aa3b, v148
	v_mul_f32_e32 v152, 0xbfb8aa3b, v152
	v_mul_f32_e32 v154, 0xbfb8aa3b, v154
	v_mul_f32_e32 v156, 0xbfb8aa3b, v156
	v_mul_f32_e32 v160, 0xbfb8aa3b, v160
	v_mul_f32_e32 v164, 0xbfb8aa3b, v164
	v_mul_f32_e32 v172, 0xbfb8aa3b, v172
	v_mul_f32_e32 v174, 0xbfb8aa3b, v174
	v_pk_mul_f32 v[128:129], v[128:129], v[172:173] op_sel_hi:[1,0]
	v_pk_mul_f32 v[126:127], v[126:127], v[172:173] op_sel_hi:[1,0]
	v_pk_mul_f32 v[124:125], v[124:125], v[172:173] op_sel_hi:[1,0]
	v_pk_mul_f32 v[122:123], v[122:123], v[172:173] op_sel_hi:[1,0]
	v_pk_mul_f32 v[170:171], v[116:117], v[172:173] op_sel_hi:[1,0]
	s_nop 0
	s_nop 0
	s_nop 0
	s_nop 0
	s_nop 0
	s_nop 0
	s_nop 0
	s_nop 0
	v_exp_f32_e32 v116, v126
	v_exp_f32_e32 v117, v122
	v_exp_f32_e32 v122, v127
	v_exp_f32_e32 v123, v123
	v_exp_f32_e32 v126, v128
	v_exp_f32_e32 v124, v124
	v_exp_f32_e32 v127, v129
	v_exp_f32_e32 v125, v125
	v_pk_mul_f32 v[114:115], v[114:115], v[172:173] op_sel_hi:[1,0]
	v_add_f32_e32 v116, 1.0, v116
	s_nop 0
	s_nop 0
	v_exp_f32_e32 v114, v114
	v_exp_f32_e32 v115, v115
	v_add_f32_e32 v117, 1.0, v117
	v_add_f32_e32 v122, 1.0, v122
	v_add_f32_e32 v123, 1.0, v123
	v_add_f32_e32 v126, 1.0, v126
	v_add_f32_e32 v124, 1.0, v124
	v_add_f32_e32 v127, 1.0, v127
	v_add_f32_e32 v125, 1.0, v125
	v_rcp_f32_e32 v116, v116
	v_rcp_f32_e32 v117, v117
	v_rcp_f32_e32 v122, v122
	v_rcp_f32_e32 v123, v123
	v_rcp_f32_e32 v126, v126
	v_rcp_f32_e32 v124, v124
	v_rcp_f32_e32 v127, v127
	v_rcp_f32_e32 v125, v125
	v_pk_mul_f32 v[120:121], v[120:121], v[172:173] op_sel_hi:[1,0]
	v_add_f32_e32 v114, 1.0, v114
	s_nop 0
	v_add_f32_e32 v115, 1.0, v115
	s_nop 0
	v_exp_f32_e32 v120, v120
	v_rcp_f32_e32 v129, v114
	v_rcp_f32_e32 v159, v115
	v_cvt_pk_bf16_f32 v114, v116, v122
	v_cvt_pk_bf16_f32 v115, v126, v127
	v_cvt_pk_bf16_f32 v116, v117, v123
	v_cvt_pk_bf16_f32 v117, v124, v125
	v_pk_mul_f32 v[118:119], v[118:119], v[172:173] op_sel_hi:[1,0]
	v_exp_f32_e32 v128, v170
	global_store_dwordx4 v[178:179], v[114:117], off
	s_nop 0
	s_nop 0
	s_nop 0
	v_exp_f32_e32 v116, v121
	s_nop 0
	v_exp_f32_e32 v118, v118
	v_exp_f32_e32 v119, v119
	v_exp_f32_e32 v117, v171
	v_add_f32_e32 v114, 1.0, v120
	v_rcp_f32_e32 v115, v114
	v_add_f32_e32 v114, 1.0, v128
	v_rcp_f32_e32 v120, v114
	v_add_f32_e32 v114, 1.0, v116
	v_pk_mul_f32 v[106:107], v[106:107], v[174:175] op_sel_hi:[1,0]
	v_add_f32_e32 v118, 1.0, v118
	v_add_f32_e32 v119, 1.0, v119
	v_rcp_f32_e32 v116, v114
	v_add_f32_e32 v114, 1.0, v117
	v_pk_mul_f32 v[110:111], v[110:111], v[174:175] op_sel_hi:[1,0]
	s_nop 0
	v_rcp_f32_e32 v118, v118
	v_rcp_f32_e32 v119, v119
	v_rcp_f32_e32 v117, v114
	v_exp_f32_e32 v106, v106
	s_nop 0
	v_exp_f32_e32 v111, v111
	v_cvt_pk_bf16_f32 v114, v118, v119
	v_cvt_pk_bf16_f32 v115, v115, v116
	v_cvt_pk_bf16_f32 v116, v129, v159
	v_cvt_pk_bf16_f32 v117, v120, v117
	v_pk_mul_f32 v[112:113], v[112:113], v[174:175] op_sel_hi:[1,0]
	v_add_f32_e32 v106, 1.0, v106
	s_nop 0
	global_store_dwordx4 v[178:179], v[114:117], off offset:256
	v_exp_f32_e32 v107, v107
	v_pk_mul_f32 v[108:109], v[108:109], v[174:175] op_sel_hi:[1,0]
	v_rcp_f32_e32 v114, v106
	v_add_f32_e32 v106, 1.0, v111
	s_nop 0
	v_exp_f32_e32 v111, v112
	s_nop 0
	v_add_f32_e32 v107, 1.0, v107
	s_nop 0
	v_exp_f32_e32 v110, v110
	v_exp_f32_e32 v108, v108
	v_rcp_f32_e32 v112, v107
	v_add_f32_e32 v107, 1.0, v111
	s_nop 0
	s_nop 0
	v_exp_f32_e32 v111, v113
	v_exp_f32_e32 v109, v109
	v_add_f32_e32 v110, 1.0, v110
	v_add_f32_e32 v108, 1.0, v108
	v_pk_mul_f32 v[98:99], v[98:99], v[174:175] op_sel_hi:[1,0]
	v_rcp_f32_e32 v110, v110
	v_rcp_f32_e32 v106, v106
	v_rcp_f32_e32 v113, v108
	v_add_f32_e32 v108, 1.0, v111
	v_add_f32_e32 v109, 1.0, v109
	v_pk_mul_f32 v[102:103], v[102:103], v[174:175] op_sel_hi:[1,0]
	s_nop 0
	v_rcp_f32_e32 v107, v107
	v_rcp_f32_e32 v108, v108
	v_rcp_f32_e32 v109, v109
	v_exp_f32_e32 v98, v98
	s_nop 0
	v_exp_f32_e32 v103, v103
	v_cvt_pk_bf16_f32 v106, v110, v106
	v_mad_i64_i32 v[110:111], s[22:23], v176, s41, v[146:147]
	v_cvt_pk_bf16_f32 v107, v107, v108
	v_cvt_pk_bf16_f32 v108, v114, v112
	v_cvt_pk_bf16_f32 v109, v113, v109
	v_lshl_add_u64 v[110:111], v[110:111], 0, v[150:151]
	v_pk_mul_f32 v[104:105], v[104:105], v[174:175] op_sel_hi:[1,0]
	v_add_f32_e32 v98, 1.0, v98
	s_nop 0
	global_store_dwordx4 v[110:111], v[106:109], off
	v_exp_f32_e32 v99, v99
	v_pk_mul_f32 v[100:101], v[100:101], v[174:175] op_sel_hi:[1,0]
	v_rcp_f32_e32 v106, v98
	v_add_f32_e32 v98, 1.0, v103
	s_nop 0
	v_exp_f32_e32 v103, v104
	v_add_f32_e32 v99, 1.0, v99
	s_nop 0
	s_nop 0
	v_exp_f32_e32 v100, v100
	v_rcp_f32_e32 v104, v99
	v_add_f32_e32 v99, 1.0, v103
	s_nop 0
	s_nop 0
	v_exp_f32_e32 v102, v102
	v_exp_f32_e32 v103, v105
	v_exp_f32_e32 v101, v101
	v_add_f32_e32 v100, 1.0, v100
	v_pk_mul_f32 v[90:91], v[90:91], v[164:165] op_sel_hi:[1,0]
	v_add_f32_e32 v102, 1.0, v102
	v_rcp_f32_e32 v105, v100
	v_add_f32_e32 v100, 1.0, v103
	v_add_f32_e32 v101, 1.0, v101
	v_pk_mul_f32 v[94:95], v[94:95], v[164:165] op_sel_hi:[1,0]
	s_nop 0
	v_rcp_f32_e32 v102, v102
	v_rcp_f32_e32 v98, v98
	v_rcp_f32_e32 v99, v99
	v_rcp_f32_e32 v100, v100
	v_rcp_f32_e32 v101, v101
	v_exp_f32_e32 v90, v90
	s_nop 0
	v_exp_f32_e32 v95, v95
	v_cvt_pk_bf16_f32 v98, v102, v98
	v_cvt_pk_bf16_f32 v99, v99, v100
	v_cvt_pk_bf16_f32 v100, v106, v104
	v_cvt_pk_bf16_f32 v101, v105, v101
	v_pk_mul_f32 v[96:97], v[96:97], v[164:165] op_sel_hi:[1,0]
	v_add_f32_e32 v90, 1.0, v90
	s_nop 0
	global_store_dwordx4 v[110:111], v[98:101], off offset:256
	v_exp_f32_e32 v91, v91
	v_pk_mul_f32 v[92:93], v[92:93], v[164:165] op_sel_hi:[1,0]
	v_rcp_f32_e32 v98, v90
	v_add_f32_e32 v90, 1.0, v95
	s_nop 0
	v_exp_f32_e32 v95, v96
	s_nop 0
	v_add_f32_e32 v91, 1.0, v91
	s_nop 0
	v_exp_f32_e32 v94, v94
	v_exp_f32_e32 v92, v92
	v_rcp_f32_e32 v96, v91
	v_add_f32_e32 v91, 1.0, v95
	s_nop 0
	s_nop 0
	v_exp_f32_e32 v95, v97
	v_exp_f32_e32 v93, v93
	v_add_f32_e32 v94, 1.0, v94
	v_add_f32_e32 v92, 1.0, v92
	v_pk_mul_f32 v[82:83], v[82:83], v[164:165] op_sel_hi:[1,0]
	v_rcp_f32_e32 v94, v94
	v_rcp_f32_e32 v90, v90
	v_rcp_f32_e32 v97, v92
	v_add_f32_e32 v92, 1.0, v95
	v_add_f32_e32 v93, 1.0, v93
	v_pk_mul_f32 v[86:87], v[86:87], v[164:165] op_sel_hi:[1,0]
	s_nop 0
	v_rcp_f32_e32 v91, v91
	v_rcp_f32_e32 v92, v92
	v_rcp_f32_e32 v93, v93
	v_exp_f32_e32 v82, v82
	s_nop 0
	v_exp_f32_e32 v87, v87
	v_cvt_pk_bf16_f32 v90, v94, v90
	v_mad_i64_i32 v[94:95], s[22:23], v162, s41, v[146:147]
	v_cvt_pk_bf16_f32 v91, v91, v92
	v_cvt_pk_bf16_f32 v92, v98, v96
	v_cvt_pk_bf16_f32 v93, v97, v93
	v_lshl_add_u64 v[94:95], v[94:95], 0, v[150:151]
	v_pk_mul_f32 v[88:89], v[88:89], v[164:165] op_sel_hi:[1,0]
	v_add_f32_e32 v82, 1.0, v82
	s_nop 0
	global_store_dwordx4 v[94:95], v[90:93], off
	v_exp_f32_e32 v83, v83
	v_pk_mul_f32 v[84:85], v[84:85], v[164:165] op_sel_hi:[1,0]
	v_rcp_f32_e32 v90, v82
	v_add_f32_e32 v82, 1.0, v87
	s_nop 0
	v_exp_f32_e32 v87, v88
	v_add_f32_e32 v83, 1.0, v83
	s_nop 0
	s_nop 0
	v_exp_f32_e32 v84, v84
	v_rcp_f32_e32 v88, v83
	v_add_f32_e32 v83, 1.0, v87
	s_nop 0
	s_nop 0
	v_exp_f32_e32 v86, v86
	v_exp_f32_e32 v87, v89
	v_exp_f32_e32 v85, v85
	v_add_f32_e32 v84, 1.0, v84
	v_pk_mul_f32 v[74:75], v[74:75], v[160:161] op_sel_hi:[1,0]
	v_add_f32_e32 v86, 1.0, v86
	v_rcp_f32_e32 v89, v84
	v_add_f32_e32 v84, 1.0, v87
	v_add_f32_e32 v85, 1.0, v85
	v_pk_mul_f32 v[78:79], v[78:79], v[160:161] op_sel_hi:[1,0]
	s_nop 0
	v_rcp_f32_e32 v86, v86
	v_rcp_f32_e32 v82, v82
	v_rcp_f32_e32 v83, v83
	v_rcp_f32_e32 v84, v84
	v_rcp_f32_e32 v85, v85
	v_exp_f32_e32 v74, v74
	s_nop 0
	v_exp_f32_e32 v79, v79
	v_cvt_pk_bf16_f32 v82, v86, v82
	v_cvt_pk_bf16_f32 v83, v83, v84
	v_cvt_pk_bf16_f32 v84, v90, v88
	v_cvt_pk_bf16_f32 v85, v89, v85
	v_pk_mul_f32 v[80:81], v[80:81], v[160:161] op_sel_hi:[1,0]
	v_add_f32_e32 v74, 1.0, v74
	s_nop 0
	global_store_dwordx4 v[94:95], v[82:85], off offset:256
	v_exp_f32_e32 v75, v75
	v_pk_mul_f32 v[76:77], v[76:77], v[160:161] op_sel_hi:[1,0]
	v_rcp_f32_e32 v82, v74
	v_add_f32_e32 v74, 1.0, v79
	s_nop 0
	v_exp_f32_e32 v79, v80
	s_nop 0
	v_add_f32_e32 v75, 1.0, v75
	s_nop 0
	v_exp_f32_e32 v78, v78
	v_exp_f32_e32 v76, v76
	v_rcp_f32_e32 v80, v75
	v_add_f32_e32 v75, 1.0, v79
	s_nop 0
	s_nop 0
	v_exp_f32_e32 v79, v81
	v_exp_f32_e32 v77, v77
	v_add_f32_e32 v78, 1.0, v78
	v_add_f32_e32 v76, 1.0, v76
	v_pk_mul_f32 v[66:67], v[66:67], v[160:161] op_sel_hi:[1,0]
	v_rcp_f32_e32 v78, v78
	v_rcp_f32_e32 v74, v74
	v_rcp_f32_e32 v81, v76
	v_add_f32_e32 v76, 1.0, v79
	v_add_f32_e32 v77, 1.0, v77
	v_pk_mul_f32 v[70:71], v[70:71], v[160:161] op_sel_hi:[1,0]
	s_nop 0
	v_rcp_f32_e32 v75, v75
	v_rcp_f32_e32 v76, v76
	v_rcp_f32_e32 v77, v77
	v_exp_f32_e32 v66, v66
	s_nop 0
	v_exp_f32_e32 v71, v71
	v_cvt_pk_bf16_f32 v74, v78, v74
	v_mad_i64_i32 v[78:79], s[22:23], v158, s41, v[146:147]
	v_cvt_pk_bf16_f32 v75, v75, v76
	v_cvt_pk_bf16_f32 v76, v82, v80
	v_cvt_pk_bf16_f32 v77, v81, v77
	v_lshl_add_u64 v[78:79], v[78:79], 0, v[150:151]
	v_pk_mul_f32 v[72:73], v[72:73], v[160:161] op_sel_hi:[1,0]
	v_add_f32_e32 v66, 1.0, v66
	s_nop 0
	global_store_dwordx4 v[78:79], v[74:77], off
	v_exp_f32_e32 v67, v67
	v_pk_mul_f32 v[68:69], v[68:69], v[160:161] op_sel_hi:[1,0]
	v_rcp_f32_e32 v74, v66
	v_add_f32_e32 v66, 1.0, v71
	s_nop 0
	v_exp_f32_e32 v71, v72
	v_add_f32_e32 v67, 1.0, v67
	s_nop 0
	s_nop 0
	v_exp_f32_e32 v68, v68
	v_rcp_f32_e32 v72, v67
	v_add_f32_e32 v67, 1.0, v71
	s_nop 0
	s_nop 0
	v_exp_f32_e32 v70, v70
	v_exp_f32_e32 v71, v73
	v_exp_f32_e32 v69, v69
	v_add_f32_e32 v68, 1.0, v68
	v_pk_mul_f32 v[58:59], v[58:59], v[156:157] op_sel_hi:[1,0]
	v_add_f32_e32 v70, 1.0, v70
	v_rcp_f32_e32 v73, v68
	v_add_f32_e32 v68, 1.0, v71
	v_add_f32_e32 v69, 1.0, v69
	v_pk_mul_f32 v[62:63], v[62:63], v[156:157] op_sel_hi:[1,0]
	s_nop 0
	v_rcp_f32_e32 v70, v70
	v_rcp_f32_e32 v66, v66
	v_rcp_f32_e32 v67, v67
	v_rcp_f32_e32 v68, v68
	v_rcp_f32_e32 v69, v69
	v_exp_f32_e32 v58, v58
	s_nop 0
	v_exp_f32_e32 v63, v63
	v_cvt_pk_bf16_f32 v66, v70, v66
	v_cvt_pk_bf16_f32 v67, v67, v68
	v_cvt_pk_bf16_f32 v68, v74, v72
	v_cvt_pk_bf16_f32 v69, v73, v69
	v_pk_mul_f32 v[64:65], v[64:65], v[156:157] op_sel_hi:[1,0]
	v_add_f32_e32 v58, 1.0, v58
	s_nop 0
	global_store_dwordx4 v[78:79], v[66:69], off offset:256
	v_exp_f32_e32 v59, v59
	v_pk_mul_f32 v[60:61], v[60:61], v[156:157] op_sel_hi:[1,0]
	v_rcp_f32_e32 v66, v58
	v_add_f32_e32 v58, 1.0, v63
	s_nop 0
	v_exp_f32_e32 v63, v64
	s_nop 0
	v_add_f32_e32 v59, 1.0, v59
	s_nop 0
	v_exp_f32_e32 v62, v62
	v_exp_f32_e32 v60, v60
	v_rcp_f32_e32 v64, v59
	v_add_f32_e32 v59, 1.0, v63
	s_nop 0
	s_nop 0
	v_exp_f32_e32 v63, v65
	v_exp_f32_e32 v61, v61
	v_add_f32_e32 v62, 1.0, v62
	v_add_f32_e32 v60, 1.0, v60
	v_pk_mul_f32 v[50:51], v[50:51], v[156:157] op_sel_hi:[1,0]
	v_rcp_f32_e32 v62, v62
	v_rcp_f32_e32 v58, v58
	v_rcp_f32_e32 v65, v60
	v_add_f32_e32 v60, 1.0, v63
	v_add_f32_e32 v61, 1.0, v61
	v_pk_mul_f32 v[54:55], v[54:55], v[156:157] op_sel_hi:[1,0]
	s_nop 0
	v_rcp_f32_e32 v59, v59
	v_rcp_f32_e32 v60, v60
	v_rcp_f32_e32 v61, v61
	v_exp_f32_e32 v50, v50
	s_nop 0
	v_exp_f32_e32 v55, v55
	v_cvt_pk_bf16_f32 v58, v62, v58
	v_mad_i64_i32 v[62:63], s[22:23], v168, s41, v[146:147]
	v_cvt_pk_bf16_f32 v59, v59, v60
	v_cvt_pk_bf16_f32 v60, v66, v64
	v_cvt_pk_bf16_f32 v61, v65, v61
	v_lshl_add_u64 v[62:63], v[62:63], 0, v[150:151]
	v_pk_mul_f32 v[56:57], v[56:57], v[156:157] op_sel_hi:[1,0]
	v_add_f32_e32 v50, 1.0, v50
	s_nop 0
	global_store_dwordx4 v[62:63], v[58:61], off
	v_exp_f32_e32 v51, v51
	v_pk_mul_f32 v[52:53], v[52:53], v[156:157] op_sel_hi:[1,0]
	v_rcp_f32_e32 v58, v50
	v_add_f32_e32 v50, 1.0, v55
	s_nop 0
	v_exp_f32_e32 v55, v56
	v_add_f32_e32 v51, 1.0, v51
	s_nop 0
	s_nop 0
	v_exp_f32_e32 v52, v52
	v_rcp_f32_e32 v56, v51
	v_add_f32_e32 v51, 1.0, v55
	s_nop 0
	s_nop 0
	v_exp_f32_e32 v54, v54
	v_exp_f32_e32 v55, v57
	v_exp_f32_e32 v53, v53
	v_add_f32_e32 v52, 1.0, v52
	v_pk_mul_f32 v[42:43], v[42:43], v[154:155] op_sel_hi:[1,0]
	v_add_f32_e32 v54, 1.0, v54
	v_rcp_f32_e32 v57, v52
	v_add_f32_e32 v52, 1.0, v55
	v_add_f32_e32 v53, 1.0, v53
	v_pk_mul_f32 v[46:47], v[46:47], v[154:155] op_sel_hi:[1,0]
	s_nop 0
	v_rcp_f32_e32 v54, v54
	v_rcp_f32_e32 v50, v50
	v_rcp_f32_e32 v51, v51
	v_rcp_f32_e32 v52, v52
	v_rcp_f32_e32 v53, v53
	v_exp_f32_e32 v42, v42
	s_nop 0
	v_exp_f32_e32 v47, v47
	v_cvt_pk_bf16_f32 v50, v54, v50
	v_cvt_pk_bf16_f32 v51, v51, v52
	v_cvt_pk_bf16_f32 v52, v58, v56
	v_cvt_pk_bf16_f32 v53, v57, v53
	v_pk_mul_f32 v[48:49], v[48:49], v[154:155] op_sel_hi:[1,0]
	v_add_f32_e32 v42, 1.0, v42
	s_nop 0
	global_store_dwordx4 v[62:63], v[50:53], off offset:256
	v_exp_f32_e32 v43, v43
	v_pk_mul_f32 v[44:45], v[44:45], v[154:155] op_sel_hi:[1,0]
	v_rcp_f32_e32 v50, v42
	v_add_f32_e32 v42, 1.0, v47
	s_nop 0
	v_exp_f32_e32 v47, v48
	s_nop 0
	v_add_f32_e32 v43, 1.0, v43
	s_nop 0
	v_exp_f32_e32 v46, v46
	v_exp_f32_e32 v44, v44
	v_rcp_f32_e32 v48, v43
	v_add_f32_e32 v43, 1.0, v47
	s_nop 0
	s_nop 0
	v_exp_f32_e32 v47, v49
	v_exp_f32_e32 v45, v45
	v_add_f32_e32 v46, 1.0, v46
	v_add_f32_e32 v44, 1.0, v44
	v_pk_mul_f32 v[34:35], v[34:35], v[154:155] op_sel_hi:[1,0]
	v_rcp_f32_e32 v46, v46
	v_rcp_f32_e32 v42, v42
	v_rcp_f32_e32 v49, v44
	v_add_f32_e32 v44, 1.0, v47
	v_add_f32_e32 v45, 1.0, v45
	v_pk_mul_f32 v[38:39], v[38:39], v[154:155] op_sel_hi:[1,0]
	s_nop 0
	v_rcp_f32_e32 v43, v43
	v_rcp_f32_e32 v44, v44
	v_rcp_f32_e32 v45, v45
	v_exp_f32_e32 v34, v34
	s_nop 0
	v_exp_f32_e32 v39, v39
	v_cvt_pk_bf16_f32 v42, v46, v42
	v_mad_i64_i32 v[46:47], s[22:23], v167, s41, v[146:147]
	v_cvt_pk_bf16_f32 v43, v43, v44
	v_cvt_pk_bf16_f32 v44, v50, v48
	v_cvt_pk_bf16_f32 v45, v49, v45
	v_lshl_add_u64 v[46:47], v[46:47], 0, v[150:151]
	v_pk_mul_f32 v[40:41], v[40:41], v[154:155] op_sel_hi:[1,0]
	v_add_f32_e32 v34, 1.0, v34
	s_nop 0
	global_store_dwordx4 v[46:47], v[42:45], off
	v_exp_f32_e32 v35, v35
	v_pk_mul_f32 v[36:37], v[36:37], v[154:155] op_sel_hi:[1,0]
	v_rcp_f32_e32 v42, v34
	v_add_f32_e32 v34, 1.0, v39
	s_nop 0
	v_exp_f32_e32 v39, v40
	v_add_f32_e32 v35, 1.0, v35
	s_nop 0
	s_nop 0
	v_exp_f32_e32 v36, v36
	v_rcp_f32_e32 v40, v35
	v_add_f32_e32 v35, 1.0, v39
	s_nop 0
	s_nop 0
	v_exp_f32_e32 v38, v38
	v_exp_f32_e32 v39, v41
	v_exp_f32_e32 v37, v37
	v_add_f32_e32 v36, 1.0, v36
	v_pk_mul_f32 v[26:27], v[26:27], v[152:153] op_sel_hi:[1,0]
	v_add_f32_e32 v38, 1.0, v38
	v_rcp_f32_e32 v41, v36
	v_add_f32_e32 v36, 1.0, v39
	v_add_f32_e32 v37, 1.0, v37
	v_pk_mul_f32 v[30:31], v[30:31], v[152:153] op_sel_hi:[1,0]
	s_nop 0
	v_rcp_f32_e32 v38, v38
	v_rcp_f32_e32 v34, v34
	v_rcp_f32_e32 v35, v35
	v_rcp_f32_e32 v36, v36
	v_rcp_f32_e32 v37, v37
	v_exp_f32_e32 v26, v26
	s_nop 0
	v_exp_f32_e32 v31, v31
	v_cvt_pk_bf16_f32 v34, v38, v34
	v_cvt_pk_bf16_f32 v35, v35, v36
	v_cvt_pk_bf16_f32 v36, v42, v40
	v_cvt_pk_bf16_f32 v37, v41, v37
	v_pk_mul_f32 v[32:33], v[32:33], v[152:153] op_sel_hi:[1,0]
	v_add_f32_e32 v26, 1.0, v26
	s_nop 0
	global_store_dwordx4 v[46:47], v[34:37], off offset:256
	v_exp_f32_e32 v27, v27
	v_pk_mul_f32 v[28:29], v[28:29], v[152:153] op_sel_hi:[1,0]
	v_rcp_f32_e32 v34, v26
	v_add_f32_e32 v26, 1.0, v31
	s_nop 0
	v_exp_f32_e32 v31, v32
	s_nop 0
	v_add_f32_e32 v27, 1.0, v27
	s_nop 0
	v_exp_f32_e32 v30, v30
	v_exp_f32_e32 v28, v28
	v_rcp_f32_e32 v32, v27
	v_add_f32_e32 v27, 1.0, v31
	s_nop 0
	s_nop 0
	v_exp_f32_e32 v31, v33
	v_exp_f32_e32 v29, v29
	v_add_f32_e32 v30, 1.0, v30
	v_add_f32_e32 v28, 1.0, v28
	v_pk_mul_f32 v[18:19], v[18:19], v[152:153] op_sel_hi:[1,0]
	v_rcp_f32_e32 v30, v30
	v_rcp_f32_e32 v26, v26
	v_rcp_f32_e32 v33, v28
	v_add_f32_e32 v28, 1.0, v31
	v_add_f32_e32 v29, 1.0, v29
	v_pk_mul_f32 v[22:23], v[22:23], v[152:153] op_sel_hi:[1,0]
	s_nop 0
	v_rcp_f32_e32 v27, v27
	v_rcp_f32_e32 v28, v28
	v_rcp_f32_e32 v29, v29
	v_exp_f32_e32 v18, v18
	s_nop 0
	v_exp_f32_e32 v23, v23
	v_cvt_pk_bf16_f32 v26, v30, v26
	v_mad_i64_i32 v[30:31], s[22:23], v166, s41, v[146:147]
	v_cvt_pk_bf16_f32 v27, v27, v28
	v_cvt_pk_bf16_f32 v28, v34, v32
	v_cvt_pk_bf16_f32 v29, v33, v29
	v_lshl_add_u64 v[30:31], v[30:31], 0, v[150:151]
	v_pk_mul_f32 v[24:25], v[24:25], v[152:153] op_sel_hi:[1,0]
	v_add_f32_e32 v18, 1.0, v18
	s_nop 0
	global_store_dwordx4 v[30:31], v[26:29], off
	v_exp_f32_e32 v19, v19
	v_pk_mul_f32 v[20:21], v[20:21], v[152:153] op_sel_hi:[1,0]
	v_rcp_f32_e32 v26, v18
	v_add_f32_e32 v18, 1.0, v23
	s_nop 0
	v_exp_f32_e32 v23, v24
	v_add_f32_e32 v19, 1.0, v19
	s_nop 0
	s_nop 0
	v_exp_f32_e32 v20, v20
	v_rcp_f32_e32 v24, v19
	v_add_f32_e32 v19, 1.0, v23
	s_nop 0
	s_nop 0
	v_exp_f32_e32 v22, v22
	v_exp_f32_e32 v23, v25
	v_exp_f32_e32 v21, v21
	v_add_f32_e32 v20, 1.0, v20
	v_pk_mul_f32 v[10:11], v[10:11], v[148:149] op_sel_hi:[1,0]
	v_add_f32_e32 v22, 1.0, v22
	v_rcp_f32_e32 v25, v20
	v_add_f32_e32 v20, 1.0, v23
	v_add_f32_e32 v21, 1.0, v21
	v_pk_mul_f32 v[14:15], v[14:15], v[148:149] op_sel_hi:[1,0]
	s_nop 0
	v_rcp_f32_e32 v22, v22
	v_rcp_f32_e32 v18, v18
	v_rcp_f32_e32 v19, v19
	v_rcp_f32_e32 v20, v20
	v_rcp_f32_e32 v21, v21
	v_exp_f32_e32 v10, v10
	s_nop 0
	v_exp_f32_e32 v15, v15
	v_cvt_pk_bf16_f32 v18, v22, v18
	v_cvt_pk_bf16_f32 v19, v19, v20
	v_cvt_pk_bf16_f32 v20, v26, v24
	v_cvt_pk_bf16_f32 v21, v25, v21
	v_pk_mul_f32 v[16:17], v[16:17], v[148:149] op_sel_hi:[1,0]
	v_add_f32_e32 v10, 1.0, v10
	s_nop 0
	global_store_dwordx4 v[30:31], v[18:21], off offset:256
	v_exp_f32_e32 v11, v11
	v_pk_mul_f32 v[12:13], v[12:13], v[148:149] op_sel_hi:[1,0]
	v_rcp_f32_e32 v18, v10
	v_add_f32_e32 v10, 1.0, v15
	s_nop 0
	v_exp_f32_e32 v15, v16
	s_nop 0
	v_add_f32_e32 v11, 1.0, v11
	s_nop 0
	v_exp_f32_e32 v14, v14
	v_exp_f32_e32 v12, v12
	v_rcp_f32_e32 v16, v11
	v_add_f32_e32 v11, 1.0, v15
	s_nop 0
	s_nop 0
	v_exp_f32_e32 v15, v17
	v_exp_f32_e32 v13, v13
	v_add_f32_e32 v14, 1.0, v14
	v_add_f32_e32 v12, 1.0, v12
	v_pk_mul_f32 v[2:3], v[2:3], v[148:149] op_sel_hi:[1,0]
	v_rcp_f32_e32 v14, v14
	v_rcp_f32_e32 v10, v10
	v_rcp_f32_e32 v17, v12
	v_add_f32_e32 v12, 1.0, v15
	v_add_f32_e32 v13, 1.0, v13
	v_pk_mul_f32 v[6:7], v[6:7], v[148:149] op_sel_hi:[1,0]
	s_nop 0
	v_rcp_f32_e32 v11, v11
	v_rcp_f32_e32 v12, v12
	v_rcp_f32_e32 v13, v13
	v_exp_f32_e32 v2, v2
	s_nop 0
	v_exp_f32_e32 v7, v7
	v_cvt_pk_bf16_f32 v10, v14, v10
	v_mad_i64_i32 v[14:15], s[22:23], v165, s41, v[146:147]
	v_cvt_pk_bf16_f32 v11, v11, v12
	v_cvt_pk_bf16_f32 v12, v18, v16
	v_cvt_pk_bf16_f32 v13, v17, v13
	v_lshl_add_u64 v[14:15], v[14:15], 0, v[150:151]
	v_pk_mul_f32 v[8:9], v[8:9], v[148:149] op_sel_hi:[1,0]
	v_add_f32_e32 v2, 1.0, v2
	s_nop 0
	global_store_dwordx4 v[14:15], v[10:13], off
	v_exp_f32_e32 v3, v3
	v_pk_mul_f32 v[4:5], v[4:5], v[148:149] op_sel_hi:[1,0]
	v_rcp_f32_e32 v10, v2
	v_add_f32_e32 v2, 1.0, v7
	s_nop 0
	v_exp_f32_e32 v7, v8
	v_add_f32_e32 v3, 1.0, v3
	s_nop 0
	s_nop 0
	v_exp_f32_e32 v4, v4
	v_rcp_f32_e32 v8, v3
	v_add_f32_e32 v3, 1.0, v7
	s_nop 0
	s_nop 0
	v_exp_f32_e32 v6, v6
	v_exp_f32_e32 v7, v9
	v_exp_f32_e32 v5, v5
	v_add_f32_e32 v4, 1.0, v4
	v_add_f32_e32 v6, 1.0, v6
	v_rcp_f32_e32 v9, v4
	v_add_f32_e32 v4, 1.0, v7
	v_add_f32_e32 v5, 1.0, v5
	v_rcp_f32_e32 v6, v6
	v_rcp_f32_e32 v2, v2
	v_rcp_f32_e32 v3, v3
	v_rcp_f32_e32 v4, v4
	v_rcp_f32_e32 v5, v5
	v_cvt_pk_bf16_f32 v2, v6, v2
	v_cvt_pk_bf16_f32 v3, v3, v4
	v_cvt_pk_bf16_f32 v4, v10, v8
	v_cvt_pk_bf16_f32 v5, v9, v5
	global_store_dwordx4 v[14:15], v[2:5], off offset:256
	s_cbranch_vccnz .LBB0_1292
	s_andn2_b64 vcc, exec, s[6:7]
	s_cbranch_vccnz .LBB0_1291
	s_barrier
	s_branch .LBB0_1291
